# v19 + latent diff attention: persistent score-bias register block (no per-tile C-init moves)
# speedup vs baseline: 1.0036x; 1.0036x over previous
.LBB0_778:
	s_andn2_b64 vcc, exec, s[4:5]
	s_cbranch_vccnz .LBB0_787
	s_add_i32 s4, s26, 0xffffff00
	s_lshr_b32 s11, s4, 7
	s_lshl_b32 s5, s26, 7
	s_lshl_b32 s4, s11, 12
	s_and_b32 s5, s5, 0xf80
	v_readlane_b32 s6, v254, 50
	s_addk_i32 s4, 0x1000
	s_or_b32 s5, s5, s6
	s_bfe_u32 s13, s26, 0x20005
	s_or_b32 s20, s5, s4
	s_mul_hi_u32 s5, s4, 0x1800
	s_mulk_i32 s4, 0x1800
	s_add_u32 s4, s83, s4
	s_addc_u32 s5, s55, s5
	s_lshl_b32 s6, s13, 7
	s_lshl_b32 s18, s13, 8
	s_add_u32 s4, s4, s18
	s_addc_u32 s5, s5, 0
	s_add_u32 s7, s4, 0x400
	s_addc_u32 s8, s5, 0
	s_add_u32 s9, s4, 0x800
	s_addc_u32 s10, s5, 0
	s_lshl_b32 s11, s11, 2
	v_readlane_b32 s48, v253, 63
	v_readlane_b32 s49, v254, 0
	s_add_i32 s48, s11, s65
	s_lshl_b32 s11, s13, 16
	s_lshl_b64 s[16:17], s[48:49], 18
	s_or_b32 s16, s16, s11
	v_readlane_b32 s11, v255, 9
	s_add_u32 s11, s11, s16
	v_readlane_b32 s12, v255, 10
	s_addc_u32 s13, s12, s17
	v_readlane_b32 s12, v255, 11
	s_add_u32 s16, s12, s16
	v_readlane_b32 s12, v255, 12
	s_addc_u32 s17, s12, s17
	s_add_u32 s18, s83, s18
	s_addc_u32 s19, s55, 0
	s_mul_i32 s33, s20, 0x1800
	s_mul_hi_u32 s21, s20, 0x1800
	s_add_u32 s33, s18, s33
	s_addc_u32 s21, s19, s21
	v_readlane_b32 s18, v254, 51
	v_readlane_b32 s19, v254, 52
	v_mov_b32_e32 v143, v209
	s_lshl_b64 s[18:19], s[18:19], 1
	s_add_u32 s18, s33, s18
	v_and_b32_e32 v151, 31, v143
	v_ashrrev_i32_e32 v10, 5, v143
	v_mul_u32_u24_e32 v0, 0xc00, v151
	s_addc_u32 s19, s21, s19
	v_lshlrev_b32_e32 v0, 1, v0
	v_mov_b32_e32 v1, v64
	v_lshlrev_b32_e32 v2, 3, v10
	v_lshl_add_u64 v[0:1], s[18:19], 0, v[0:1]
	v_ashrrev_i32_e32 v3, 31, v2
	v_lshl_add_u64 v[0:1], v[2:3], 1, v[0:1]
	s_barrier
	global_load_dwordx4 v[126:129], v[0:1], off
	global_load_dwordx4 v[130:133], v[0:1], off offset:32
	global_load_dwordx4 v[134:137], v[0:1], off offset:64
	global_load_dwordx4 v[138:141], v[0:1], off offset:96
	v_ashrrev_i32_e32 v0, 4, v143
	v_lshlrev_b32_e32 v3, 3, v143
	v_bfe_u32 v2, v143, 2, 2
	v_bfe_u32 v4, v143, 1, 1
	v_lshlrev_b32_e32 v142, 2, v10
	v_and_b32_e32 v180, 8, v3
	v_lshlrev_b32_e32 v3, 1, v0
	v_readlane_b32 s12, v254, 35
	v_and_b32_e32 v1, 15, v143
	v_lshlrev_b32_e32 v5, 6, v2
	v_add_u32_e32 v181, s12, v0
	v_lshlrev_b32_e32 v0, 2, v0
	v_or_b32_e32 v2, v142, v2
	v_and_or_b32 v3, v3, 2, v4
	v_bitop3_b32 v0, v0, v1, 12 bitop3:0x6c
	v_xor_b32_e32 v1, v181, v143
	v_add_u32_e32 v182, 4, v181
	v_lshlrev_b32_e32 v183, 8, v2
	v_lshlrev_b32_e32 v2, 4, v3
	s_movk_i32 s12, 0x80
	v_readlane_b32 s50, v254, 1
	v_readlane_b32 s51, v254, 2
	v_lshlrev_b32_e32 v144, 4, v0
	v_lshlrev_b32_e32 v0, 4, v1
	v_xor_b32_e32 v1, v182, v143
	v_bitop3_b32 v188, v2, s12, v5 bitop3:0x36
	s_movk_i32 s12, 0xc0
	s_mov_b32 s48, s20
	v_mov_b32_e32 v145, v64
	v_or_b32_e32 v186, v2, v5
	v_bitop3_b32 v187, v2, 64, v5 bitop3:0x36
	v_bitop3_b32 v189, v2, s12, v5 bitop3:0x36
	v_and_b32_e32 v176, 0xf0, v0
	v_lshlrev_b32_e32 v0, 4, v1
	v_mov_b64_e32 v[2:3], s[4:5]
	v_writelane_b32 v253, s48, 63
	v_mov_b32_e32 v177, v64
	v_and_b32_e32 v178, 0xf0, v0
	v_writelane_b32 v254, s49, 0
	v_lshl_add_u64 v[0:1], s[4:5], 0, v[144:145]
	v_mad_i64_i32 v[4:5], s[4:5], v181, s64, v[2:3]
	v_writelane_b32 v254, s50, 1
	v_mad_i64_i32 v[6:7], s[4:5], v181, s64, v[0:1]
	v_mad_i64_i32 v[8:9], s[4:5], v182, s64, v[2:3]
	v_lshl_add_u64 v[4:5], v[4:5], 0, v[176:177]
	v_writelane_b32 v254, s51, 2
	v_mov_b32_e32 v179, v64
	s_mov_b64 s[40:41], 0x800
	v_lshl_add_u64 v[4:5], v[4:5], 0, s[84:85]
	s_waitcnt vmcnt(3)
	s_waitcnt vmcnt(2)
	s_waitcnt vmcnt(1)
	s_waitcnt vmcnt(0)
	s_waitcnt vmcnt(0) expcnt(0) lgkmcnt(0)
	s_mov_b32 s4, m0
	s_mov_b32 m0, s25
	s_nop 0
	global_load_lds_dwordx4 v[4:5], off
	s_mov_b32 m0, s4
	v_readlane_b32 s5, v254, 36
	v_lshl_add_u64 v[6:7], v[6:7], 0, s[40:41]
	v_lshl_add_u64 v[8:9], v[8:9], 0, v[178:179]
	s_mov_b32 s4, m0
	s_mov_b32 m0, s5
	s_nop 0
	global_load_lds_dwordx4 v[6:7], off
	s_mov_b32 m0, s4
	v_readlane_b32 s5, v254, 37
	v_lshl_add_u64 v[8:9], v[8:9], 0, s[84:85]
	s_mov_b32 s4, m0
	s_mov_b32 m0, s5
	s_nop 0
	global_load_lds_dwordx4 v[8:9], off
	s_mov_b32 m0, s4
	v_add_u32_e32 v6, 64, v181
	v_mad_i64_i32 v[4:5], s[4:5], v182, s64, v[0:1]
	v_lshl_add_u64 v[4:5], v[4:5], 0, s[40:41]
	v_readlane_b32 s5, v254, 25
	s_mov_b32 s4, m0
	s_mov_b32 m0, s5
	s_nop 0
	global_load_lds_dwordx4 v[4:5], off
	s_mov_b32 m0, s4
	v_mov_b32_e32 v62, v64
	v_mad_i64_i32 v[4:5], s[4:5], v6, s64, v[2:3]
	v_lshl_add_u64 v[4:5], v[4:5], 0, v[176:177]
	v_lshl_add_u64 v[4:5], v[4:5], 0, s[84:85]
	v_readlane_b32 s5, v254, 54
	s_mov_b32 s4, m0
	s_mov_b32 m0, s5
	s_nop 0
	global_load_lds_dwordx4 v[4:5], off
	s_mov_b32 m0, s4
	v_mov_b32_e32 v63, v64
	v_mad_i64_i32 v[4:5], s[4:5], v6, s64, v[0:1]
	v_lshl_add_u64 v[4:5], v[4:5], 0, s[40:41]
	v_readlane_b32 s5, v254, 55
	v_add_u32_e32 v6, 0x44, v181
	s_mov_b32 s4, m0
	s_mov_b32 m0, s5
	s_nop 0
	global_load_lds_dwordx4 v[4:5], off
	s_mov_b32 m0, s4
	v_mov_b32_e32 v76, v64
	v_mad_i64_i32 v[4:5], s[4:5], v6, s64, v[2:3]
	v_lshl_add_u64 v[4:5], v[4:5], 0, v[178:179]
	v_lshl_add_u64 v[4:5], v[4:5], 0, s[84:85]
	v_readlane_b32 s5, v254, 56
	s_mov_b32 s4, m0
	s_mov_b32 m0, s5
	s_nop 0
	global_load_lds_dwordx4 v[4:5], off
	s_mov_b32 m0, s4
	v_mov_b32_e32 v77, v64
	v_mad_i64_i32 v[4:5], s[4:5], v6, s64, v[0:1]
	v_lshl_add_u64 v[4:5], v[4:5], 0, s[40:41]
	v_readlane_b32 s5, v254, 57
	v_add_u32_e32 v6, 0x80, v181
	s_mov_b32 s4, m0
	s_mov_b32 m0, s5
	s_nop 0
	global_load_lds_dwordx4 v[4:5], off
	s_mov_b32 m0, s4
	v_mov_b32_e32 v65, v64
	v_mad_i64_i32 v[4:5], s[4:5], v6, s64, v[2:3]
	v_lshl_add_u64 v[4:5], v[4:5], 0, v[176:177]
	v_lshl_add_u64 v[4:5], v[4:5], 0, s[84:85]
	v_readlane_b32 s5, v254, 58
	s_mov_b32 s4, m0
	s_mov_b32 m0, s5
	s_nop 0
	global_load_lds_dwordx4 v[4:5], off
	s_mov_b32 m0, s4
	v_mov_b32_e32 v66, v64
	v_mad_i64_i32 v[4:5], s[4:5], v6, s64, v[0:1]
	v_lshl_add_u64 v[4:5], v[4:5], 0, s[40:41]
	v_readlane_b32 s5, v254, 59
	s_mov_b32 s4, m0
	s_mov_b32 m0, s5
	s_nop 0
	global_load_lds_dwordx4 v[4:5], off
	s_mov_b32 m0, s4
	v_add_u32_e32 v4, 0x84, v181
	v_mad_i64_i32 v[2:3], s[4:5], v4, s64, v[2:3]
	v_lshl_add_u64 v[2:3], v[2:3], 0, v[178:179]
	v_readlane_b32 s5, v254, 60
	v_lshl_add_u64 v[2:3], v[2:3], 0, s[84:85]
	s_mov_b32 s4, m0
	s_mov_b32 m0, s5
	s_nop 0
	global_load_lds_dwordx4 v[2:3], off
	s_mov_b32 m0, s4
	v_mov_b32_e32 v67, v64
	v_mad_i64_i32 v[0:1], s[4:5], v4, s64, v[0:1]
	v_lshl_add_u64 v[0:1], v[0:1], 0, s[40:41]
	v_readlane_b32 s5, v254, 61
	s_mov_b32 s4, m0
	s_mov_b32 m0, s5
	s_nop 0
	global_load_lds_dwordx4 v[0:1], off
	s_mov_b32 m0, s4
	v_mov_b32_e32 v68, v64
	v_readlane_b32 s4, v254, 53
	v_mov_b32_e32 v69, v64
	v_mov_b32_e32 v70, v64
	v_add_u32_e32 v0, s4, v10
	v_bitop3_b32 v1, v0, v143, 15 bitop3:0x78
	v_lshlrev_b32_e32 v191, 4, v1
	v_add_u32_e32 v1, 2, v0
	v_bitop3_b32 v1, v1, v143, 15 bitop3:0x78
	v_lshlrev_b32_e32 v192, 4, v1
	v_add_u32_e32 v1, 4, v0
	v_add_u32_e32 v0, 6, v0
	v_bitop3_b32 v1, v1, v143, 15 bitop3:0x78
	v_bitop3_b32 v0, v0, v143, 15 bitop3:0x78
	v_lshlrev_b32_e32 v193, 4, v1
	v_lshlrev_b32_e32 v194, 4, v0
	v_mov_b32_e32 v71, v64
	v_mov_b32_e32 v72, v64
	v_mov_b32_e32 v73, v64
	v_mov_b32_e32 v74, v64
	v_mov_b32_e32 v75, v64
	v_mov_b64_e32 v[92:93], v[76:77]
	v_mov_b64_e32 v[32:33], v[62:63]
	v_mov_b64_e32 v[16:17], v[62:63]
	v_mov_b64_e32 v[0:1], v[62:63]
	s_mov_b32 s18, 3
	v_lshlrev_b32_e32 v190, 8, v151
	s_mov_b32 s4, 0
	v_mov_b32_e32 v196, 0xf149f2ca
	v_mov_b32_e32 v195, 0
	v_mov_b64_e32 v[90:91], v[74:75]
	v_mov_b64_e32 v[88:89], v[72:73]
	v_mov_b64_e32 v[86:87], v[70:71]
	v_mov_b64_e32 v[84:85], v[68:69]
	v_mov_b64_e32 v[82:83], v[66:67]
	v_mov_b64_e32 v[80:81], v[64:65]
	v_mov_b64_e32 v[78:79], v[62:63]
	v_mov_b64_e32 v[34:35], v[64:65]
	v_mov_b64_e32 v[36:37], v[66:67]
	v_mov_b64_e32 v[38:39], v[68:69]
	v_mov_b64_e32 v[40:41], v[70:71]
	v_mov_b64_e32 v[42:43], v[72:73]
	v_mov_b64_e32 v[44:45], v[74:75]
	v_mov_b64_e32 v[46:47], v[76:77]
	v_mov_b64_e32 v[18:19], v[64:65]
	v_mov_b64_e32 v[20:21], v[66:67]
	v_mov_b64_e32 v[22:23], v[68:69]
	v_mov_b64_e32 v[24:25], v[70:71]
	v_mov_b64_e32 v[26:27], v[72:73]
	v_mov_b64_e32 v[28:29], v[74:75]
	v_mov_b64_e32 v[30:31], v[76:77]
	v_mov_b64_e32 v[2:3], v[64:65]
	v_mov_b64_e32 v[4:5], v[66:67]
	v_mov_b64_e32 v[6:7], v[68:69]
	v_mov_b64_e32 v[8:9], v[70:71]
	v_mov_b64_e32 v[10:11], v[72:73]
	v_mov_b64_e32 v[12:13], v[74:75]
	v_mov_b64_e32 v[14:15], v[76:77]
	v_cmp_lt_f32_e32 vcc, s14, v196
	s_nop 1
	v_cndmask_b32_e64 v232, 0, -v196, vcc
	v_mov_b32_e32 v233, v232
	v_mov_b32_e32 v234, v232
	v_mov_b32_e32 v235, v232
	v_mov_b32_e32 v236, v232
	v_mov_b32_e32 v237, v232
	v_mov_b32_e32 v238, v232
	v_mov_b32_e32 v239, v232
	v_mov_b32_e32 v240, v232
	v_mov_b32_e32 v241, v232
	v_mov_b32_e32 v242, v232
	v_mov_b32_e32 v243, v232
	v_mov_b32_e32 v244, v232
	v_mov_b32_e32 v245, v232
	v_mov_b32_e32 v246, v232
	v_mov_b32_e32 v247, v232
	s_branch .LBB0_781

.LBB0_781:
	s_add_i32 s5, s18, -3
	s_min_i32 s19, s18, 0x43
	s_cmp_lt_u32 s5, 61
	s_cselect_b64 s[20:21], -1, 0
	s_and_b64 s[40:41], s[20:21], exec
	s_cselect_b32 s5, 0, 0xffffffc0
	s_add_i32 s5, s5, s19
	s_and_b64 s[20:21], s[20:21], exec
	s_cselect_b32 s21, s8, s13
	s_cselect_b32 s20, s7, s11
	s_cselect_b32 s41, s10, s17
	s_cselect_b32 s40, s9, s16
	s_cselect_b32 s19, s64, 0x100
	s_lshl_b32 s5, s5, 6
	v_add_u32_e32 v54, s5, v181
	v_mov_b64_e32 v[50:51], s[20:21]
	s_waitcnt vmcnt(8)
	s_add_i32 s33, s4, 0x18000
	v_mad_i64_i32 v[52:53], s[20:21], s19, v54, v[50:51]
	s_waitcnt lgkmcnt(0)
	s_barrier
	s_and_b32 s33, s33, 0x18000
	v_lshl_add_u64 v[48:49], s[40:41], 0, v[144:145]
	v_lshl_add_u64 v[52:53], v[52:53], 0, v[176:177]
	s_add_i32 s33, s33, s25
	s_mov_b32 s20, m0
	s_mov_b32 m0, s33
	s_nop 0
	global_load_lds_dwordx4 v[52:53], off
	s_mov_b32 m0, s20
	s_add_i32 s40, s33, 0x4000
	v_mad_i64_i32 v[52:53], s[20:21], s19, v54, v[48:49]
	s_mov_b32 s20, m0
	s_mov_b32 m0, s40
	s_nop 0
	global_load_lds_dwordx4 v[52:53], off
	s_mov_b32 m0, s20
	v_add_u32_e32 v52, s5, v182
	v_mad_i64_i32 v[50:51], s[20:21], s19, v52, v[50:51]
	v_lshl_add_u64 v[50:51], v[50:51], 0, v[178:179]
	s_add_i32 s5, s33, 0x400
	s_mov_b32 s20, m0
	s_mov_b32 m0, s5
	s_nop 0
	global_load_lds_dwordx4 v[50:51], off
	s_mov_b32 m0, s20
	s_addk_i32 s33, 0x4400
	v_mad_i64_i32 v[48:49], s[20:21], s19, v52, v[48:49]
	s_mov_b32 s5, m0
	s_mov_b32 m0, s33
	s_nop 0
	global_load_lds_dwordx4 v[48:49], off
	s_mov_b32 m0, s5
	s_and_b32 s5, s4, 0x18000
	s_add_i32 s5, s5, 0
	v_add_u32_e32 v48, s5, v190
	v_add_u32_e32 v49, v48, v191
	v_add_u32_e32 v51, v48, v193
	v_add_u32_e32 v50, v48, v192
	ds_read_b128 v[66:69], v49
	ds_read_b128 v[70:73], v50
	v_add_u32_e32 v230, v48, v194
	ds_read_b128 v[74:77], v51
	ds_read_b128 v[94:97], v230
	ds_read_b128 v[198:201], v49 offset:8192
	ds_read_b128 v[202:205], v50 offset:8192
	ds_read_b128 v[226:229], v51 offset:8192
	s_waitcnt lgkmcnt(6)
	s_nop 0
	v_mfma_f32_32x32x16_bf16 v[48:63], v[66:69], v[126:129], v[232:247]
	s_waitcnt lgkmcnt(5)
	v_mfma_f32_32x32x16_bf16 v[48:63], v[70:73], v[130:133], v[48:63]
	ds_read_b128 v[70:73], v230 offset:8192
	s_waitcnt lgkmcnt(5)
	v_mfma_f32_32x32x16_bf16 v[48:63], v[74:77], v[134:137], v[48:63]
	s_waitcnt lgkmcnt(4)
	v_mfma_f32_32x32x16_bf16 v[48:63], v[94:97], v[138:141], v[48:63]
	s_nop 7
	s_nop 3
	v_max_f32_e32 v65, v49, v49
	v_max_f32_e32 v66, v48, v48
	s_waitcnt lgkmcnt(3)
	v_mfma_f32_32x32x16_bf16 v[94:109], v[198:201], v[126:129], v[232:247]
	v_max_f32_e32 v65, v66, v65
	v_max3_f32 v65, v65, v50, v51
	v_max3_f32 v65, v65, v52, v53
	v_max3_f32 v65, v65, v54, v55
	v_max3_f32 v65, v65, v56, v57
	v_max3_f32 v65, v65, v58, v59
	v_max3_f32 v65, v65, v60, v61
	s_waitcnt lgkmcnt(2)
	v_mfma_f32_32x32x16_bf16 v[94:109], v[202:205], v[130:133], v[94:109]
	v_max3_f32 v65, v65, v62, v63
	v_add_f32_e32 v66, 0x41000000, v196
	s_waitcnt lgkmcnt(1)
	v_mfma_f32_32x32x16_bf16 v[94:109], v[226:229], v[134:137], v[94:109]
	s_waitcnt lgkmcnt(0)
	v_mfma_f32_32x32x16_bf16 v[94:109], v[70:73], v[138:141], v[94:109]
	s_nop 11
	v_max3_f32 v65, v65, v94, v95
	v_max3_f32 v65, v65, v96, v97
	v_max3_f32 v65, v65, v98, v99
	v_max3_f32 v65, v65, v100, v101
	v_max3_f32 v65, v65, v102, v103
	v_max3_f32 v65, v65, v104, v105
	v_max3_f32 v65, v65, v106, v107
	v_max3_f32 v65, v65, v108, v109
	v_sub_f32_e32 v65, v65, v232
	v_cmp_gt_f32_e32 vcc, v65, v66
	s_cbranch_vccz .LBB0_780
	ds_bpermute_b32 v66, v214, v65
	s_waitcnt lgkmcnt(0)
	v_max3_f32 v65, v196, v65, v66
	v_sub_f32_e32 v66, v196, v65
	v_exp_f32_e32 v66, v66
	v_add_f32_e32 v68, v232, v65
	v_pk_add_f32 v[48:49], v[48:49], v[68:69] op_sel_hi:[1,0] neg_lo:[0,1] neg_hi:[0,1]
	v_pk_add_f32 v[50:51], v[50:51], v[68:69] op_sel_hi:[1,0] neg_lo:[0,1] neg_hi:[0,1]
	v_pk_mul_f32 v[92:93], v[92:93], v[66:67] op_sel_hi:[1,0]
	v_pk_mul_f32 v[90:91], v[90:91], v[66:67] op_sel_hi:[1,0]
	v_pk_mul_f32 v[88:89], v[88:89], v[66:67] op_sel_hi:[1,0]
	v_pk_mul_f32 v[86:87], v[86:87], v[66:67] op_sel_hi:[1,0]
	v_pk_mul_f32 v[84:85], v[84:85], v[66:67] op_sel_hi:[1,0]
	v_pk_mul_f32 v[82:83], v[82:83], v[66:67] op_sel_hi:[1,0]
	v_pk_mul_f32 v[80:81], v[80:81], v[66:67] op_sel_hi:[1,0]
	v_pk_mul_f32 v[78:79], v[78:79], v[66:67] op_sel_hi:[1,0]
	v_pk_mul_f32 v[46:47], v[46:47], v[66:67] op_sel_hi:[1,0]
	v_pk_mul_f32 v[44:45], v[44:45], v[66:67] op_sel_hi:[1,0]
	v_pk_mul_f32 v[42:43], v[42:43], v[66:67] op_sel_hi:[1,0]
	v_pk_mul_f32 v[40:41], v[40:41], v[66:67] op_sel_hi:[1,0]
	v_pk_mul_f32 v[38:39], v[38:39], v[66:67] op_sel_hi:[1,0]
	v_pk_mul_f32 v[36:37], v[36:37], v[66:67] op_sel_hi:[1,0]
	v_pk_mul_f32 v[34:35], v[34:35], v[66:67] op_sel_hi:[1,0]
	v_pk_mul_f32 v[32:33], v[32:33], v[66:67] op_sel_hi:[1,0]
	v_pk_mul_f32 v[30:31], v[30:31], v[66:67] op_sel_hi:[1,0]
	v_pk_mul_f32 v[28:29], v[28:29], v[66:67] op_sel_hi:[1,0]
	v_pk_mul_f32 v[26:27], v[26:27], v[66:67] op_sel_hi:[1,0]
	v_pk_mul_f32 v[24:25], v[24:25], v[66:67] op_sel_hi:[1,0]
	v_pk_mul_f32 v[22:23], v[22:23], v[66:67] op_sel_hi:[1,0]
	v_pk_mul_f32 v[20:21], v[20:21], v[66:67] op_sel_hi:[1,0]
	v_pk_mul_f32 v[18:19], v[18:19], v[66:67] op_sel_hi:[1,0]
	v_pk_mul_f32 v[16:17], v[16:17], v[66:67] op_sel_hi:[1,0]
	v_pk_mul_f32 v[14:15], v[14:15], v[66:67] op_sel_hi:[1,0]
	v_pk_mul_f32 v[12:13], v[12:13], v[66:67] op_sel_hi:[1,0]
	v_pk_mul_f32 v[10:11], v[10:11], v[66:67] op_sel_hi:[1,0]
	v_pk_mul_f32 v[8:9], v[8:9], v[66:67] op_sel_hi:[1,0]
	v_pk_mul_f32 v[6:7], v[6:7], v[66:67] op_sel_hi:[1,0]
	v_pk_mul_f32 v[4:5], v[4:5], v[66:67] op_sel_hi:[1,0]
	v_pk_mul_f32 v[2:3], v[2:3], v[66:67] op_sel_hi:[1,0]
	v_pk_mul_f32 v[0:1], v[0:1], v[66:67] op_sel_hi:[1,0]
	v_pk_add_f32 v[52:53], v[52:53], v[68:69] op_sel_hi:[1,0] neg_lo:[0,1] neg_hi:[0,1]
	v_pk_add_f32 v[54:55], v[54:55], v[68:69] op_sel_hi:[1,0] neg_lo:[0,1] neg_hi:[0,1]
	v_pk_add_f32 v[56:57], v[56:57], v[68:69] op_sel_hi:[1,0] neg_lo:[0,1] neg_hi:[0,1]
	v_pk_add_f32 v[58:59], v[58:59], v[68:69] op_sel_hi:[1,0] neg_lo:[0,1] neg_hi:[0,1]
	v_pk_add_f32 v[60:61], v[60:61], v[68:69] op_sel_hi:[1,0] neg_lo:[0,1] neg_hi:[0,1]
	v_pk_add_f32 v[62:63], v[62:63], v[68:69] op_sel_hi:[1,0] neg_lo:[0,1] neg_hi:[0,1]
	v_sub_f32_e32 v94, v94, v68
	v_sub_f32_e32 v95, v95, v68
	v_pk_add_f32 v[96:97], v[96:97], v[68:69] op_sel_hi:[1,0] neg_lo:[0,1] neg_hi:[0,1]
	v_pk_add_f32 v[98:99], v[98:99], v[68:69] op_sel_hi:[1,0] neg_lo:[0,1] neg_hi:[0,1]
	v_pk_add_f32 v[100:101], v[100:101], v[68:69] op_sel_hi:[1,0] neg_lo:[0,1] neg_hi:[0,1]
	v_pk_add_f32 v[102:103], v[102:103], v[68:69] op_sel_hi:[1,0] neg_lo:[0,1] neg_hi:[0,1]
	v_pk_add_f32 v[104:105], v[104:105], v[68:69] op_sel_hi:[1,0] neg_lo:[0,1] neg_hi:[0,1]
	v_pk_add_f32 v[106:107], v[106:107], v[68:69] op_sel_hi:[1,0] neg_lo:[0,1] neg_hi:[0,1]
	v_pk_add_f32 v[108:109], v[108:109], v[68:69] op_sel_hi:[1,0] neg_lo:[0,1] neg_hi:[0,1]
	v_mul_f32_e32 v195, v195, v66
	v_mov_b32_e32 v196, v65
	v_cmp_lt_f32_e32 vcc, s14, v196
	s_nop 1
	v_cndmask_b32_e64 v232, 0, -v196, vcc
	v_mov_b32_e32 v233, v232
	v_mov_b32_e32 v234, v232
	v_mov_b32_e32 v235, v232
	v_mov_b32_e32 v236, v232
	v_mov_b32_e32 v237, v232
	v_mov_b32_e32 v238, v232
	v_mov_b32_e32 v239, v232
	v_mov_b32_e32 v240, v232
	v_mov_b32_e32 v241, v232
	v_mov_b32_e32 v242, v232
	v_mov_b32_e32 v243, v232
	v_mov_b32_e32 v244, v232
	v_mov_b32_e32 v245, v232
	v_mov_b32_e32 v246, v232
	v_mov_b32_e32 v247, v232
	s_branch .LBB0_780
